# ra_items S2: step A(it+1) runs in the same barrier interval as step B(it): 6 intervals instead of 10 per item (on v44)
# baseline (speedup 1.0000x reference)
.LBB0_389:
	s_mov_b32 s46, vcc_lo
	v_add3_u32 v73, s49, v202, v227
	v_add3_u32 v74, s48, v204, v227
	ds_read_b128 v[100:103], v73
	ds_read_b128 v[118:121], v74
	ds_read_b128 v[122:125], v74 offset:2304
	ds_read_b128 v[126:129], v73 offset:64
	ds_read_b128 v[174:177], v74 offset:64
	ds_read_b128 v[178:181], v74 offset:2368
	s_waitcnt lgkmcnt(4)
	v_mfma_f32_16x16x32_bf16 v[118:121], v[100:103], v[118:121], 0
	s_waitcnt lgkmcnt(3)
	v_mfma_f32_16x16x32_bf16 v[100:103], v[100:103], v[122:125], 0
	s_waitcnt lgkmcnt(1)
	v_mfma_f32_16x16x32_bf16 v[118:121], v[126:129], v[174:177], v[118:121]
	s_waitcnt lgkmcnt(0)
	v_mfma_f32_16x16x32_bf16 v[100:103], v[126:129], v[178:181], v[100:103]
	s_nop 4
	v_add3_u32 v73, s81, v204, v140
	v_cvt_pk_bf16_f32 v74, v118, v119
	v_cvt_pk_bf16_f32 v75, v120, v121
	ds_write_b64 v73, v[74:75]
	v_add3_u32 v73, s81, v205, v140
	s_nop 0
	v_cvt_pk_bf16_f32 v74, v100, v101
	v_cvt_pk_bf16_f32 v75, v102, v103
	ds_write_b64 v73, v[74:75]
	v_add3_u32 v74, s46, v141, v212
	v_bfe_u32 v73, v118, 16, 1
	v_add3_u32 v73, v118, v73, s86
	ds_write_b16_d16_hi v74, v73
	v_bfe_u32 v73, v119, 16, 1
	v_add3_u32 v73, v119, v73, s86
	ds_write_b16_d16_hi v74, v73 offset:144
	v_bfe_u32 v73, v120, 16, 1
	v_add3_u32 v73, v120, v73, s86
	ds_write_b16_d16_hi v74, v73 offset:288
	v_bfe_u32 v73, v121, 16, 1
	v_add3_u32 v73, v121, v73, s86
	ds_write_b16_d16_hi v74, v73 offset:432
	v_bfe_u32 v73, v100, 16, 1
	v_add3_u32 v73, v100, v73, s86
	ds_write_b16_d16_hi v74, v73 offset:32
	v_bfe_u32 v73, v101, 16, 1
	v_add3_u32 v73, v101, v73, s86
	ds_write_b16_d16_hi v74, v73 offset:176
	v_bfe_u32 v73, v102, 16, 1
	v_add3_u32 v73, v102, v73, s86
	ds_write_b16_d16_hi v74, v73 offset:320
	v_bfe_u32 v73, v103, 16, 1
	v_add3_u32 v73, v103, v73, s86
	ds_write_b16_d16_hi v74, v73 offset:464
	s_waitcnt lgkmcnt(0)
	s_barrier
	v_add3_u32 v182, s81, v202, v227
	v_add_u32_e32 v183, s1, v204
	v_add_u32_e32 v184, v183, v227
	v_add3_u32 v185, s92, v140, v204
	v_add_u32_e32 v183, v183, v140
	v_add3_u32 v73, s46, v202, v227
	v_add3_u32 v74, s81, v204, v227
	ds_read_b128 v[186:189], v182
	ds_read_b128 v[190:193], v184
	ds_read_b128 v[234:237], v184 offset:2304
	ds_read_b128 v[100:103], v73
	ds_read_b128 v[118:121], v74
	ds_read_b128 v[122:125], v74 offset:2304
	ds_read_b128 v[238:241], v182 offset:64
	ds_read_b128 v[242:245], v184 offset:64
	ds_read_b128 v[246:249], v184 offset:2368
	ds_read_b128 v[126:129], v73 offset:64
	ds_read_b128 v[174:177], v74 offset:64
	ds_read_b128 v[178:181], v74 offset:2368
	ds_read_b64 v[250:251], v183
	ds_read_b64 v[252:253], v183 offset:2304
	s_waitcnt lgkmcnt(12)
	v_mfma_f32_16x16x32_bf16 v[190:193], v[186:189], v[190:193], 0
	s_waitcnt lgkmcnt(11)
	v_mfma_f32_16x16x32_bf16 v[186:189], v[186:189], v[234:237], 0
	s_waitcnt lgkmcnt(9)
	v_mfma_f32_16x16x32_bf16 v[118:121], v[100:103], v[118:121], 0
	s_waitcnt lgkmcnt(8)
	v_mfma_f32_16x16x32_bf16 v[100:103], v[100:103], v[122:125], 0
	s_waitcnt lgkmcnt(6)
	v_mfma_f32_16x16x32_bf16 v[190:193], v[238:241], v[242:245], v[190:193]
	s_waitcnt lgkmcnt(5)
	v_mfma_f32_16x16x32_bf16 v[186:189], v[238:241], v[246:249], v[186:189]
	s_waitcnt lgkmcnt(3)
	v_mfma_f32_16x16x32_bf16 v[118:121], v[126:129], v[174:177], v[118:121]
	s_waitcnt lgkmcnt(2)
	v_mfma_f32_16x16x32_bf16 v[100:103], v[126:129], v[178:181], v[100:103]
	s_waitcnt lgkmcnt(0)
	v_lshlrev_b32_e32 v194, 16, v250
	v_and_b32_e32 v195, 0xffff0000, v250
	v_lshlrev_b32_e32 v250, 16, v251
	v_and_b32_e32 v251, 0xffff0000, v251
	v_pk_add_f32 v[190:191], v[190:191], v[194:195]
	v_pk_add_f32 v[250:251], v[192:193], v[250:251]
	v_cvt_pk_bf16_f32 v190, v190, v191
	v_cvt_pk_bf16_f32 v191, v250, v251
	ds_write_b64 v185, v[190:191]
	v_lshlrev_b32_e32 v194, 16, v252
	v_and_b32_e32 v195, 0xffff0000, v252
	v_lshlrev_b32_e32 v252, 16, v253
	v_and_b32_e32 v253, 0xffff0000, v253
	v_pk_add_f32 v[186:187], v[186:187], v[194:195]
	v_pk_add_f32 v[252:253], v[188:189], v[252:253]
	v_cvt_pk_bf16_f32 v186, v186, v187
	v_cvt_pk_bf16_f32 v187, v252, v253
	ds_write_b64 v185, v[186:187] offset:2304
	v_add3_u32 v73, s48, v204, v140
	v_cvt_pk_bf16_f32 v74, v118, v119
	v_cvt_pk_bf16_f32 v75, v120, v121
	ds_write_b64 v73, v[74:75]
	v_add3_u32 v73, s48, v205, v140
	s_nop 0
	v_cvt_pk_bf16_f32 v74, v100, v101
	v_cvt_pk_bf16_f32 v75, v102, v103
	ds_write_b64 v73, v[74:75]
	v_add3_u32 v74, s49, v141, v212
	v_bfe_u32 v73, v118, 16, 1
	v_add3_u32 v73, v118, v73, s86
	ds_write_b16_d16_hi v74, v73
	v_bfe_u32 v73, v119, 16, 1
	v_add3_u32 v73, v119, v73, s86
	ds_write_b16_d16_hi v74, v73 offset:144
	v_bfe_u32 v73, v120, 16, 1
	v_add3_u32 v73, v120, v73, s86
	ds_write_b16_d16_hi v74, v73 offset:288
	v_bfe_u32 v73, v121, 16, 1
	v_add3_u32 v73, v121, v73, s86
	ds_write_b16_d16_hi v74, v73 offset:432
	v_bfe_u32 v73, v100, 16, 1
	v_add3_u32 v73, v100, v73, s86
	ds_write_b16_d16_hi v74, v73 offset:32
	v_bfe_u32 v73, v101, 16, 1
	v_add3_u32 v73, v101, v73, s86
	ds_write_b16_d16_hi v74, v73 offset:176
	v_bfe_u32 v73, v102, 16, 1
	v_add3_u32 v73, v102, v73, s86
	ds_write_b16_d16_hi v74, v73 offset:320
	v_bfe_u32 v73, v103, 16, 1
	v_add3_u32 v73, v103, v73, s86
	ds_write_b16_d16_hi v74, v73 offset:464
	s_waitcnt lgkmcnt(0)
	s_barrier
	v_add3_u32 v182, s48, v202, v227
	v_add_u32_e32 v183, s92, v204
	v_add_u32_e32 v184, v183, v227
	v_add3_u32 v185, s1, v140, v204
	v_add_u32_e32 v183, v183, v140
	v_add3_u32 v73, s49, v202, v227
	v_add3_u32 v74, s48, v204, v227
	ds_read_b128 v[186:189], v182
	ds_read_b128 v[190:193], v184
	ds_read_b128 v[234:237], v184 offset:2304
	ds_read_b128 v[100:103], v73
	ds_read_b128 v[118:121], v74
	ds_read_b128 v[122:125], v74 offset:2304
	ds_read_b128 v[238:241], v182 offset:64
	ds_read_b128 v[242:245], v184 offset:64
	ds_read_b128 v[246:249], v184 offset:2368
	ds_read_b128 v[126:129], v73 offset:64
	ds_read_b128 v[174:177], v74 offset:64
	ds_read_b128 v[178:181], v74 offset:2368
	ds_read_b64 v[250:251], v183
	ds_read_b64 v[252:253], v183 offset:2304
	s_waitcnt lgkmcnt(12)
	v_mfma_f32_16x16x32_bf16 v[190:193], v[186:189], v[190:193], 0
	s_waitcnt lgkmcnt(11)
	v_mfma_f32_16x16x32_bf16 v[186:189], v[186:189], v[234:237], 0
	s_waitcnt lgkmcnt(9)
	v_mfma_f32_16x16x32_bf16 v[118:121], v[100:103], v[118:121], 0
	s_waitcnt lgkmcnt(8)
	v_mfma_f32_16x16x32_bf16 v[100:103], v[100:103], v[122:125], 0
	s_waitcnt lgkmcnt(6)
	v_mfma_f32_16x16x32_bf16 v[190:193], v[238:241], v[242:245], v[190:193]
	s_waitcnt lgkmcnt(5)
	v_mfma_f32_16x16x32_bf16 v[186:189], v[238:241], v[246:249], v[186:189]
	s_waitcnt lgkmcnt(3)
	v_mfma_f32_16x16x32_bf16 v[118:121], v[126:129], v[174:177], v[118:121]
	s_waitcnt lgkmcnt(2)
	v_mfma_f32_16x16x32_bf16 v[100:103], v[126:129], v[178:181], v[100:103]
	s_waitcnt lgkmcnt(0)
	v_lshlrev_b32_e32 v194, 16, v250
	v_and_b32_e32 v195, 0xffff0000, v250
	v_lshlrev_b32_e32 v250, 16, v251
	v_and_b32_e32 v251, 0xffff0000, v251
	v_pk_add_f32 v[190:191], v[190:191], v[194:195]
	v_pk_add_f32 v[250:251], v[192:193], v[250:251]
	v_cvt_pk_bf16_f32 v190, v190, v191
	v_cvt_pk_bf16_f32 v191, v250, v251
	ds_write_b64 v185, v[190:191]
	v_lshlrev_b32_e32 v194, 16, v252
	v_and_b32_e32 v195, 0xffff0000, v252
	v_lshlrev_b32_e32 v252, 16, v253
	v_and_b32_e32 v253, 0xffff0000, v253
	v_pk_add_f32 v[186:187], v[186:187], v[194:195]
	v_pk_add_f32 v[252:253], v[188:189], v[252:253]
	v_cvt_pk_bf16_f32 v186, v186, v187
	v_cvt_pk_bf16_f32 v187, v252, v253
	ds_write_b64 v185, v[186:187] offset:2304
	v_add3_u32 v73, s81, v204, v140
	v_cvt_pk_bf16_f32 v74, v118, v119
	v_cvt_pk_bf16_f32 v75, v120, v121
	ds_write_b64 v73, v[74:75]
	v_add3_u32 v73, s81, v205, v140
	s_nop 0
	v_cvt_pk_bf16_f32 v74, v100, v101
	v_cvt_pk_bf16_f32 v75, v102, v103
	ds_write_b64 v73, v[74:75]
	v_add3_u32 v74, s46, v141, v212
	v_bfe_u32 v73, v118, 16, 1
	v_add3_u32 v73, v118, v73, s86
	ds_write_b16_d16_hi v74, v73
	v_bfe_u32 v73, v119, 16, 1
	v_add3_u32 v73, v119, v73, s86
	ds_write_b16_d16_hi v74, v73 offset:144
	v_bfe_u32 v73, v120, 16, 1
	v_add3_u32 v73, v120, v73, s86
	ds_write_b16_d16_hi v74, v73 offset:288
	v_bfe_u32 v73, v121, 16, 1
	v_add3_u32 v73, v121, v73, s86
	ds_write_b16_d16_hi v74, v73 offset:432
	v_bfe_u32 v73, v100, 16, 1
	v_add3_u32 v73, v100, v73, s86
	ds_write_b16_d16_hi v74, v73 offset:32
	v_bfe_u32 v73, v101, 16, 1
	v_add3_u32 v73, v101, v73, s86
	ds_write_b16_d16_hi v74, v73 offset:176
	v_bfe_u32 v73, v102, 16, 1
	v_add3_u32 v73, v102, v73, s86
	ds_write_b16_d16_hi v74, v73 offset:320
	v_bfe_u32 v73, v103, 16, 1
	v_add3_u32 v73, v103, v73, s86
	ds_write_b16_d16_hi v74, v73 offset:464
	s_waitcnt lgkmcnt(0)
	s_barrier
	v_add3_u32 v182, s81, v202, v227
	v_add_u32_e32 v183, s1, v204
	v_add_u32_e32 v184, v183, v227
	v_add3_u32 v185, s92, v140, v204
	v_add_u32_e32 v183, v183, v140
	v_add3_u32 v73, s46, v202, v227
	v_add3_u32 v74, s81, v204, v227
	ds_read_b128 v[186:189], v182
	ds_read_b128 v[190:193], v184
	ds_read_b128 v[234:237], v184 offset:2304
	ds_read_b128 v[100:103], v73
	ds_read_b128 v[118:121], v74
	ds_read_b128 v[122:125], v74 offset:2304
	ds_read_b128 v[238:241], v182 offset:64
	ds_read_b128 v[242:245], v184 offset:64
	ds_read_b128 v[246:249], v184 offset:2368
	ds_read_b128 v[126:129], v73 offset:64
	ds_read_b128 v[174:177], v74 offset:64
	ds_read_b128 v[178:181], v74 offset:2368
	ds_read_b64 v[250:251], v183
	ds_read_b64 v[252:253], v183 offset:2304
	s_waitcnt lgkmcnt(12)
	v_mfma_f32_16x16x32_bf16 v[190:193], v[186:189], v[190:193], 0
	s_waitcnt lgkmcnt(11)
	v_mfma_f32_16x16x32_bf16 v[186:189], v[186:189], v[234:237], 0
	s_waitcnt lgkmcnt(9)
	v_mfma_f32_16x16x32_bf16 v[118:121], v[100:103], v[118:121], 0
	s_waitcnt lgkmcnt(8)
	v_mfma_f32_16x16x32_bf16 v[100:103], v[100:103], v[122:125], 0
	s_waitcnt lgkmcnt(6)
	v_mfma_f32_16x16x32_bf16 v[190:193], v[238:241], v[242:245], v[190:193]
	s_waitcnt lgkmcnt(5)
	v_mfma_f32_16x16x32_bf16 v[186:189], v[238:241], v[246:249], v[186:189]
	s_waitcnt lgkmcnt(3)
	v_mfma_f32_16x16x32_bf16 v[118:121], v[126:129], v[174:177], v[118:121]
	s_waitcnt lgkmcnt(2)
	v_mfma_f32_16x16x32_bf16 v[100:103], v[126:129], v[178:181], v[100:103]
	s_waitcnt lgkmcnt(0)
	v_lshlrev_b32_e32 v194, 16, v250
	v_and_b32_e32 v195, 0xffff0000, v250
	v_lshlrev_b32_e32 v250, 16, v251
	v_and_b32_e32 v251, 0xffff0000, v251
	v_pk_add_f32 v[190:191], v[190:191], v[194:195]
	v_pk_add_f32 v[250:251], v[192:193], v[250:251]
	v_cvt_pk_bf16_f32 v190, v190, v191
	v_cvt_pk_bf16_f32 v191, v250, v251
	ds_write_b64 v185, v[190:191]
	v_lshlrev_b32_e32 v194, 16, v252
	v_and_b32_e32 v195, 0xffff0000, v252
	v_lshlrev_b32_e32 v252, 16, v253
	v_and_b32_e32 v253, 0xffff0000, v253
	v_pk_add_f32 v[186:187], v[186:187], v[194:195]
	v_pk_add_f32 v[252:253], v[188:189], v[252:253]
	v_cvt_pk_bf16_f32 v186, v186, v187
	v_cvt_pk_bf16_f32 v187, v252, v253
	ds_write_b64 v185, v[186:187] offset:2304
	v_add3_u32 v73, s48, v204, v140
	v_cvt_pk_bf16_f32 v74, v118, v119
	v_cvt_pk_bf16_f32 v75, v120, v121
	ds_write_b64 v73, v[74:75]
	v_add3_u32 v73, s48, v205, v140
	s_nop 0
	v_cvt_pk_bf16_f32 v74, v100, v101
	v_cvt_pk_bf16_f32 v75, v102, v103
	ds_write_b64 v73, v[74:75]
	v_add3_u32 v74, s49, v141, v212
	v_bfe_u32 v73, v118, 16, 1
	v_add3_u32 v73, v118, v73, s86
	ds_write_b16_d16_hi v74, v73
	v_bfe_u32 v73, v119, 16, 1
	v_add3_u32 v73, v119, v73, s86
	ds_write_b16_d16_hi v74, v73 offset:144
	v_bfe_u32 v73, v120, 16, 1
	v_add3_u32 v73, v120, v73, s86
	ds_write_b16_d16_hi v74, v73 offset:288
	v_bfe_u32 v73, v121, 16, 1
	v_add3_u32 v73, v121, v73, s86
	ds_write_b16_d16_hi v74, v73 offset:432
	v_bfe_u32 v73, v100, 16, 1
	v_add3_u32 v73, v100, v73, s86
	ds_write_b16_d16_hi v74, v73 offset:32
	v_bfe_u32 v73, v101, 16, 1
	v_add3_u32 v73, v101, v73, s86
	ds_write_b16_d16_hi v74, v73 offset:176
	v_bfe_u32 v73, v102, 16, 1
	v_add3_u32 v73, v102, v73, s86
	ds_write_b16_d16_hi v74, v73 offset:320
	v_bfe_u32 v73, v103, 16, 1
	v_add3_u32 v73, v103, v73, s86
	ds_write_b16_d16_hi v74, v73 offset:464
	s_waitcnt lgkmcnt(0)
	s_barrier
	v_add3_u32 v182, s48, v202, v227
	v_add_u32_e32 v183, s92, v204
	v_add_u32_e32 v184, v183, v227
	v_add3_u32 v185, s1, v140, v204
	v_add_u32_e32 v183, v183, v140
	v_add3_u32 v73, s49, v202, v227
	v_add3_u32 v74, s48, v204, v227
	ds_read_b128 v[186:189], v182
	ds_read_b128 v[190:193], v184
	ds_read_b128 v[234:237], v184 offset:2304
	ds_read_b128 v[100:103], v73
	ds_read_b128 v[118:121], v74
	ds_read_b128 v[122:125], v74 offset:2304
	ds_read_b128 v[238:241], v182 offset:64
	ds_read_b128 v[242:245], v184 offset:64
	ds_read_b128 v[246:249], v184 offset:2368
	ds_read_b128 v[126:129], v73 offset:64
	ds_read_b128 v[174:177], v74 offset:64
	ds_read_b128 v[178:181], v74 offset:2368
	ds_read_b64 v[250:251], v183
	ds_read_b64 v[252:253], v183 offset:2304
	s_waitcnt lgkmcnt(12)
	v_mfma_f32_16x16x32_bf16 v[190:193], v[186:189], v[190:193], 0
	s_waitcnt lgkmcnt(11)
	v_mfma_f32_16x16x32_bf16 v[186:189], v[186:189], v[234:237], 0
	s_waitcnt lgkmcnt(9)
	v_mfma_f32_16x16x32_bf16 v[118:121], v[100:103], v[118:121], 0
	s_waitcnt lgkmcnt(8)
	v_mfma_f32_16x16x32_bf16 v[100:103], v[100:103], v[122:125], 0
	s_waitcnt lgkmcnt(6)
	v_mfma_f32_16x16x32_bf16 v[190:193], v[238:241], v[242:245], v[190:193]
	s_waitcnt lgkmcnt(5)
	v_mfma_f32_16x16x32_bf16 v[186:189], v[238:241], v[246:249], v[186:189]
	s_waitcnt lgkmcnt(3)
	v_mfma_f32_16x16x32_bf16 v[118:121], v[126:129], v[174:177], v[118:121]
	s_waitcnt lgkmcnt(2)
	v_mfma_f32_16x16x32_bf16 v[100:103], v[126:129], v[178:181], v[100:103]
	s_waitcnt lgkmcnt(0)
	v_lshlrev_b32_e32 v194, 16, v250
	v_and_b32_e32 v195, 0xffff0000, v250
	v_lshlrev_b32_e32 v250, 16, v251
	v_and_b32_e32 v251, 0xffff0000, v251
	v_pk_add_f32 v[190:191], v[190:191], v[194:195]
	v_pk_add_f32 v[250:251], v[192:193], v[250:251]
	v_cvt_pk_bf16_f32 v190, v190, v191
	v_cvt_pk_bf16_f32 v191, v250, v251
	ds_write_b64 v185, v[190:191]
	v_lshlrev_b32_e32 v194, 16, v252
	v_and_b32_e32 v195, 0xffff0000, v252
	v_lshlrev_b32_e32 v252, 16, v253
	v_and_b32_e32 v253, 0xffff0000, v253
	v_pk_add_f32 v[186:187], v[186:187], v[194:195]
	v_pk_add_f32 v[252:253], v[188:189], v[252:253]
	v_cvt_pk_bf16_f32 v186, v186, v187
	v_cvt_pk_bf16_f32 v187, v252, v253
	ds_write_b64 v185, v[186:187] offset:2304
	v_add3_u32 v73, s81, v204, v140
	v_cvt_pk_bf16_f32 v74, v118, v119
	v_cvt_pk_bf16_f32 v75, v120, v121
	ds_write_b64 v73, v[74:75]
	v_add3_u32 v73, s81, v205, v140
	s_nop 0
	v_cvt_pk_bf16_f32 v74, v100, v101
	v_cvt_pk_bf16_f32 v75, v102, v103
	ds_write_b64 v73, v[74:75]
	v_add3_u32 v74, s46, v141, v212
	v_bfe_u32 v73, v118, 16, 1
	v_add3_u32 v73, v118, v73, s86
	ds_write_b16_d16_hi v74, v73
	v_bfe_u32 v73, v119, 16, 1
	v_add3_u32 v73, v119, v73, s86
	ds_write_b16_d16_hi v74, v73 offset:144
	v_bfe_u32 v73, v120, 16, 1
	v_add3_u32 v73, v120, v73, s86
	ds_write_b16_d16_hi v74, v73 offset:288
	v_bfe_u32 v73, v121, 16, 1
	v_add3_u32 v73, v121, v73, s86
	ds_write_b16_d16_hi v74, v73 offset:432
	v_bfe_u32 v73, v100, 16, 1
	v_add3_u32 v73, v100, v73, s86
	ds_write_b16_d16_hi v74, v73 offset:32
	v_bfe_u32 v73, v101, 16, 1
	v_add3_u32 v73, v101, v73, s86
	ds_write_b16_d16_hi v74, v73 offset:176
	v_bfe_u32 v73, v102, 16, 1
	v_add3_u32 v73, v102, v73, s86
	ds_write_b16_d16_hi v74, v73 offset:320
	v_bfe_u32 v73, v103, 16, 1
	v_add3_u32 v73, v103, v73, s86
	ds_write_b16_d16_hi v74, v73 offset:464
	s_waitcnt lgkmcnt(0)
	s_barrier
	v_add3_u32 v182, s81, v202, v227
	v_add_u32_e32 v183, s1, v204
	v_add_u32_e32 v184, v183, v227
	v_add3_u32 v185, s92, v140, v204
	v_add_u32_e32 v183, v183, v140
	ds_read_b128 v[186:189], v182
	ds_read_b128 v[190:193], v184
	ds_read_b128 v[234:237], v184 offset:2304
	ds_read_b128 v[238:241], v182 offset:64
	ds_read_b128 v[242:245], v184 offset:64
	ds_read_b128 v[246:249], v184 offset:2368
	ds_read_b64 v[250:251], v183
	ds_read_b64 v[252:253], v183 offset:2304
	s_waitcnt lgkmcnt(6)
	v_mfma_f32_16x16x32_bf16 v[190:193], v[186:189], v[190:193], 0
	s_waitcnt lgkmcnt(5)
	v_mfma_f32_16x16x32_bf16 v[186:189], v[186:189], v[234:237], 0
	s_waitcnt lgkmcnt(3)
	v_mfma_f32_16x16x32_bf16 v[190:193], v[238:241], v[242:245], v[190:193]
	s_waitcnt lgkmcnt(2)
	v_mfma_f32_16x16x32_bf16 v[186:189], v[238:241], v[246:249], v[186:189]
	s_waitcnt lgkmcnt(0)
	s_nop 4
	v_lshlrev_b32_e32 v194, 16, v250
	v_and_b32_e32 v195, 0xffff0000, v250
	v_lshlrev_b32_e32 v250, 16, v251
	v_and_b32_e32 v251, 0xffff0000, v251
	v_pk_add_f32 v[190:191], v[190:191], v[194:195]
	v_pk_add_f32 v[250:251], v[192:193], v[250:251]
	v_cvt_pk_bf16_f32 v190, v190, v191
	v_cvt_pk_bf16_f32 v191, v250, v251
	ds_write_b64 v185, v[190:191]
	v_lshlrev_b32_e32 v194, 16, v252
	v_and_b32_e32 v195, 0xffff0000, v252
	v_lshlrev_b32_e32 v252, 16, v253
	v_and_b32_e32 v253, 0xffff0000, v253
	v_pk_add_f32 v[186:187], v[186:187], v[194:195]
	v_pk_add_f32 v[252:253], v[188:189], v[252:253]
	v_cvt_pk_bf16_f32 v186, v186, v187
	v_cvt_pk_bf16_f32 v187, v252, v253
	ds_write_b64 v185, v[186:187] offset:2304
	s_waitcnt lgkmcnt(0)
	s_barrier
	ds_read_b128 v[100:103], v71
	ds_read_b128 v[118:121], v76 offset:27648
	ds_read_b128 v[122:125], v76 offset:29952
	v_add_u32_e32 v79, v200, v205
	s_lshl_b32 s0, s80, 5
	s_or_b32 s92, s0, s87
	s_waitcnt lgkmcnt(1)
	v_mfma_f32_16x16x32_bf16 v[118:121], v[100:103], v[118:121], 0
	s_mov_b64 s[46:47], -1
	s_cmpk_lt_i32 s80, 0x100
	s_waitcnt lgkmcnt(0)
	v_mfma_f32_16x16x32_bf16 v[100:103], v[100:103], v[122:125], 0
	ds_read_b128 v[122:125], v71 offset:64
	ds_read_b128 v[126:129], v76 offset:27712
	ds_read_b128 v[174:177], v76 offset:30016
	s_waitcnt lgkmcnt(1)
	v_mfma_f32_16x16x32_bf16 v[118:121], v[122:125], v[126:129], v[118:121]
	s_waitcnt lgkmcnt(0)
	v_mfma_f32_16x16x32_bf16 v[100:103], v[122:125], v[174:177], v[100:103]
	ds_read_b128 v[122:125], v228
	ds_read_b128 v[126:129], v76 offset:64512
	ds_read_b128 v[174:177], v79 offset:64512
	s_nop 2
	v_cvt_pk_bf16_f32 v74, v118, v119
	s_waitcnt lgkmcnt(1)
	v_mfma_f32_16x16x32_bf16 v[126:129], v[122:125], v[126:129], 0
	v_cvt_pk_bf16_f32 v75, v120, v121
	s_waitcnt lgkmcnt(0)
	v_mfma_f32_16x16x32_bf16 v[122:125], v[122:125], v[174:177], 0
	ds_read_b128 v[174:177], v228 offset:64
	ds_read_b128 v[178:181], v76 offset:64576
	ds_read_b128 v[182:185], v79 offset:64576
	ds_write_b64 v213, v[74:75]
	v_cvt_pk_bf16_f32 v74, v100, v101
	s_waitcnt lgkmcnt(2)
	v_mfma_f32_16x16x32_bf16 v[126:129], v[174:177], v[178:181], v[126:129]
	v_cvt_pk_bf16_f32 v75, v102, v103
	ds_write_b64 v72, v[74:75] offset:2304
	s_waitcnt lgkmcnt(2)
	v_mfma_f32_16x16x32_bf16 v[122:125], v[174:177], v[182:185], v[122:125]
	s_nop 3
	v_cvt_pk_bf16_f32 v72, v126, v127
	v_cvt_pk_bf16_f32 v73, v128, v129
	ds_write_b64 v214, v[72:73]
	s_nop 0
	v_cvt_pk_bf16_f32 v72, v122, v123
	v_cvt_pk_bf16_f32 v73, v124, v125
	ds_write_b64 v229, v[72:73] offset:2304
	s_waitcnt lgkmcnt(0)
	s_barrier
	ds_read_b128 v[72:75], v71
	ds_read_b128 v[100:103], v207
	ds_read_b128 v[118:121], v230 offset:2304
	s_waitcnt lgkmcnt(1)
	v_mfma_f32_16x16x32_bf16 v[100:103], v[72:75], v[100:103], 0
	s_waitcnt lgkmcnt(0)
	v_mfma_f32_16x16x32_bf16 v[72:75], v[72:75], v[118:121], 0
	ds_read_b128 v[118:121], v71 offset:64
	ds_read_b128 v[122:125], v207 offset:64
	ds_read_b128 v[126:129], v230 offset:2368
	s_waitcnt lgkmcnt(1)
	v_mfma_f32_16x16x32_bf16 v[100:103], v[118:121], v[122:125], v[100:103]
	s_waitcnt lgkmcnt(0)
	v_mfma_f32_16x16x32_bf16 v[72:75], v[118:121], v[126:129], v[72:75]
	s_nop 5
	v_cvt_pk_bf16_f32 v100, v100, v101
	v_cvt_pk_bf16_f32 v101, v102, v103
	ds_write_b64 v215, v[100:101] offset:9216
	v_cvt_pk_bf16_f32 v72, v72, v73
	v_cvt_pk_bf16_f32 v73, v74, v75
	ds_write_b64 v215, v[72:73] offset:11520
	s_waitcnt lgkmcnt(0)
	s_barrier
	s_cbranch_scc1 .LBB0_392
	ds_read_b128 v[100:103], v233
	ds_read_b128 v[72:75], v233 offset:64
	s_lshl_b64 s[0:1], s[92:93], 13
	s_mov_b64 s[46:47], 0
